# weight-prep part B of layers 1-3 moved into the input-projection tail; layers 1-3 skip phase 0 and its grid barrier
# speedup vs baseline: 1.0316x; 1.0042x over previous
; #define PHASE_BEGIN KP p = (KP)__builtin_amdgcn_kernarg_segment_ptr(); asm volatile("" : "+s"(p)); unsigned char* ws = p->ws; const int G = gridDim.x, c = obid(); (void)G; (void)c; (void)ws;
; __global__ void __launch_bounds__(512) mega(Params p_unused, int ph_lo, int ph_hi) {
;     ...
;         for (int rep = 0; rep < REP0; ++rep) { PHASE_BEGIN
;             if (rep) __syncthreads();
;             convert_weights(lds, p, l, wv); bias_gemv(lds, p, l, wv); if (l == 0) init_h(p, wv); }
;         xcd_barrier(xbar, wv);
.LBB0_97:
	s_cmp_eq_u32 s90, 0
	s_cbranch_scc1 .Lp0_full
	s_mul_hi_u32 s0, s90, 0x36000
	v_writelane_b32 v255, s0, 39
	s_mul_i32 s0, s90, 0x36000
	v_writelane_b32 v255, s0, 40
	s_mov_b32 s0, 0
	v_writelane_b32 v255, s0, 41
	v_writelane_b32 v255, s0, 42
	s_mov_b32 s91, s77
	s_movk_i32 s89, 0x900
	s_branch .Lp1_entry

;     __device__ bool next(int i, Unit& u) const {
;         const long L = (long)i * G + c; if (L >= nwg) return false;
;         int wgid = (int)L; { const int q = nwg / NXCD, r = nwg % NXCD, xcd = wgid % NXCD, off = wgid / NXCD; wgid = (xcd < r ? xcd * (q + 1) : r * (q + 1) + (xcd - r) * q) + off; }
;         const int nig = WGM * nN, gid = wgid / nig, fm = gid * WGM, gsz = (nM - fm) < WGM ? (nM - fm) : WGM;
;         u.pm = fm + ((wgid % nig) % gsz); u.pn = (wgid % nig) / gsz; return true;
; template <class EpiT, class Sched>
; __device__ __forceinline__ void gemm_phase(LAS unsigned char* lds, const Gemm g, const Sched& S, const EpiT& E, int wv) {
;     ...
;     Unit cur, nxt; int ui = 0;
;     if (!S.next(0, cur)) return;
.Lp1_entry:
	v_readlane_b32 s0, v255, 0
	v_readlane_b32 s1, v255, 1
	s_waitcnt lgkmcnt(0)
	s_barrier
	s_load_dwordx2 s[0:1], s[0:1], 0xd8
	s_mov_b32 s6, s79
	s_ashr_i32 s7, s6, 31
	s_cmpk_lt_i32 s6, 0x948
	v_mbcnt_lo_u32_b32 v8, -1, 0
	v_mbcnt_hi_u32_b32 v8, -1, v8
	s_cselect_b64 s[2:3], -1, 0
	v_or_b32_e32 v192, s67, v8
	s_and_b64 vcc, exec, s[2:3]
	v_readfirstlane_b32 s14, v192
	s_cbranch_vccz .LBB0_229
	s_lshr_b32 s4, s7, 29
	s_add_i32 s4, s6, s4
	s_ashr_i32 s5, s4, 3
	s_and_b32 s4, s4, -8
	s_sub_i32 s4, s6, s4
	s_cmp_lt_i32 s4, 0
	s_movk_i32 s8, 0x12a
	s_cselect_b32 s8, s8, 0x129
	s_mul_i32 s4, s4, s8
	s_add_i32 s4, s4, s5
	s_mul_hi_i32 s5, s4, 0x3e0f83e1
	s_lshr_b32 s8, s5, 31
	s_ashr_i32 s5, s5, 6
	s_add_i32 s5, s5, s8
	s_lshl_b32 s8, s5, 3
	s_mulk_i32 s5, 0x108
	s_sub_i32 s4, s4, s5
	s_bfe_u32 s5, s4, 0x3001c
	s_add_i32 s5, s4, s5
	s_sext_i32_i16 s9, s5
	s_and_b32 s5, s5, 0xfff8
	s_sub_i32 s4, s4, s5
	s_sext_i32_i16 s4, s4
	s_add_i32 s24, s8, s4
	s_ashr_i32 s4, s9, 3

; #define LAS __attribute__((address_space(3)))
; #define otid() ((wv << 6) | olane())
; __device__ __forceinline__ void convert_weights(LAS unsigned char* lds, KP p, int l, int wv) {
;     unsigned char* ws = p->ws;
;     const int tid_ = otid(); const int lane = tid_ & 63, wid = tid_ >> 6;
;     LAS float* scr = (LAS float*)(lds + wid * 8704);
;     const int gw = blockIdx.x * 8 + wid, NGW = gridDim.x * 8;
;     constexpr int I_IN = 16 * (DIN / 32), I_UQ = 6 * 24, I_UKV = 4 * 32, I_BR = 8 * 32, I_O = 16 * 32, I_F1 = 16 * 128, I_F2 = 64 * 32;
;     constexpr int NIT = I_IN + I_UQ + I_UKV + 3 * I_BR + I_O + I_F1 + I_F2;
;     const int BIG = 1 << 30;
;     for (int it = gw; it < NIT; it += NGW) {
;         int r = it;
;         if (r < I_IN) { tr_item(p->w_in + (size_t)l * DM * DIN, DIN, (bf16_t*)(ws + WS_WIN), DM, 0, NGATE0, NPM - NGATE0, 1, 0, scr, r, lane); continue; } r -= I_IN;
;         if (r < I_UQ) { const int nb = r % 24, hh = nb / 3, part = nb % 3, dest = part < 2 ? (2 * hh + part) * 32 : 512 + 32 * hh;
;             tr_item(p->w_uq + (size_t)l * 384 * 768, 768, (bf16_t*)(ws + WS_WUQ), 384, dest - 32 * nb, BIG, 0, 1, 0, scr, r, lane); continue; } r -= I_UQ;
;         if (r < I_UKV) { tr_item(p->w_ukv + (size_t)l * 256 * 1024, 1024, (bf16_t*)(ws + WS_WUKV), 256, 0, BIG, 0, 1, 0, scr, r, lane); continue; } r -= I_UKV;
;         if (r < 3 * I_BR) { const int z3 = r / I_BR, z = z3 == 2 ? 3 : z3; tr_item(p->w_branch + ((size_t)l * 4 + z) * 512 * 1024, 1024, (bf16_t*)(ws + WS_WBR), 512, z * 1024, BIG, 0, 1, 0, scr, r % I_BR, lane); continue; } r -= 3 * I_BR;
;         if (r < I_O) { tr_item(p->w_o + (size_t)l * DM * DM, DM, (bf16_t*)(ws + WS_WO4), 4096, 0, BIG, 0, 1, 0, scr, r, lane); continue; } r -= I_O;
;         if (r < I_F1) { tr_item(p->w_ff1 + (size_t)l * DM * DFF, DFF, (bf16_t*)(ws + WS_WF1), DM, 0, BIG, 0, 1, 0, scr, r, lane); continue; } r -= I_F1;
;         tr_item(p->w_ff2 + (size_t)l * DFF * DM, DM, (bf16_t*)(ws + WS_WF2), DFF, 0, BIG, 0, 1, 0, scr, r, lane);
.LBB0_317:
	s_cmp_eq_u32 s90, 0
	s_cbranch_scc1 .Lp0b_skip
	s_cmp_lt_u32 s79, 0x48
	s_cbranch_scc1 .Lp0b_skip
	v_readlane_b32 s0, v255, 6
	v_readlane_b32 s1, v255, 7
	v_readlane_b32 s2, v255, 23
	v_readlane_b32 s3, v255, 24
	v_readlane_b32 s4, v255, 25
	v_readlane_b32 s5, v255, 26
	v_readlane_b32 s6, v255, 29
	v_readlane_b32 s7, v255, 30
	s_nop 3
	v_writelane_b32 v255, s60, 49
	v_writelane_b32 v255, s66, 50
	v_writelane_b32 v255, s0, 51
	v_writelane_b32 v255, s1, 52
	v_writelane_b32 v255, s2, 53
	v_writelane_b32 v255, s3, 54
	v_writelane_b32 v255, s4, 55
	v_writelane_b32 v255, s5, 56
	v_writelane_b32 v255, s6, 57
	v_writelane_b32 v255, s7, 58
	s_sub_i32 s79, s79, 0x48
	s_movk_i32 s60, 0xb8
	s_mov_b32 s66, 0x17000
	s_movk_i32 s89, 0x47ff
	s_lshl_b32 s0, s79, 3
	s_lshl_b32 s1, s79, 9
	s_mov_b32 s2, 0x170000
	s_mov_b32 s3, 0
	s_mov_b32 s4, 0x5c0000
	s_movk_i32 s6, 0x5c0
	v_writelane_b32 v255, s0, 6
	v_writelane_b32 v255, s1, 7
	v_writelane_b32 v255, s2, 23
	v_writelane_b32 v255, s3, 24
	v_writelane_b32 v255, s4, 25
	v_writelane_b32 v255, s3, 26
	v_writelane_b32 v255, s6, 29
	v_writelane_b32 v255, s3, 30

; __global__ void __launch_bounds__(512) mega(Params p_unused, int ph_lo, int ph_hi) {
;     ...
;             pg8::gemm_phase(lds, g, S, E, wv); }
;         xcd_barrier(xbar, wv);
.Lb_exit:
	v_readlane_b32 s79, v255, 37
	v_readlane_b32 s60, v255, 49
	v_readlane_b32 s66, v255, 50
	v_readlane_b32 s0, v255, 51
	v_readlane_b32 s1, v255, 52
	v_readlane_b32 s2, v255, 53
	v_readlane_b32 s3, v255, 54
	v_readlane_b32 s4, v255, 55
	v_readlane_b32 s5, v255, 56
	v_readlane_b32 s6, v255, 57
	v_readlane_b32 s7, v255, 58
	s_movk_i32 s89, 0x900
	s_nop 3
	v_writelane_b32 v255, s0, 6
	v_writelane_b32 v255, s1, 7
	v_writelane_b32 v255, s2, 23
	v_writelane_b32 v255, s3, 24
	v_writelane_b32 v255, s4, 25
	v_writelane_b32 v255, s5, 26
	v_writelane_b32 v255, s6, 29
	v_writelane_b32 v255, s7, 30
